# GEMM K loops: static priority raise of the leading half-workgroup (waves 0..3) instead of the trailing half
# baseline (speedup 1.0000x reference)
.LBB0_162:
	s_ashr_i32 s15, s14, 31
	s_lshl_b64 s[16:17], s[14:15], 20
	s_add_u32 s16, s29, s16
	s_addc_u32 s17, s30, s17
	s_and_b64 s[18:19], s[0:1], exec
	s_cselect_b32 s15, s17, s23
	s_cselect_b32 s54, s16, s22
	s_ashr_i32 s13, s12, 31
	s_lshl_b64 s[18:19], s[12:13], 22
	s_add_u32 s13, s8, s18
	s_addc_u32 s26, s9, s19
	s_ashr_i32 s18, s14, 3
	s_ashr_i32 s19, s18, 31
	s_lshl_b64 s[18:19], s[18:19], 12
	s_add_u32 s18, s13, s18
	s_addc_u32 s19, s26, s19
	s_and_b64 s[26:27], s[0:1], exec
	s_cselect_b32 s13, s19, s25
	s_cselect_b32 s55, s18, s24
	s_add_u32 s22, s22, 0x80080
	s_addc_u32 s23, s23, 0
	s_add_u32 s56, s24, 0x100
	v_mov_b32_e32 v0, 0
	s_addc_u32 s57, s25, 0
	s_mov_b32 s58, -2
	v_mov_b32_e32 v1, v0
	v_mov_b32_e32 v2, v0
	v_mov_b32_e32 v3, v0
	v_mov_b32_e32 v4, v0
	v_mov_b32_e32 v5, v0
	v_mov_b32_e32 v6, v0
	v_mov_b32_e32 v7, v0
	v_mov_b32_e32 v8, v0
	v_mov_b32_e32 v9, v0
	v_mov_b32_e32 v10, v0
	v_mov_b32_e32 v11, v0
	v_mov_b32_e32 v16, v0
	v_mov_b32_e32 v17, v0
	v_mov_b32_e32 v18, v0
	v_mov_b32_e32 v19, v0
	v_mov_b32_e32 v24, v0
	v_mov_b32_e32 v25, v0
	v_mov_b32_e32 v26, v0
	v_mov_b32_e32 v27, v0
	v_mov_b32_e32 v32, v0
	v_mov_b32_e32 v33, v0
	v_mov_b32_e32 v34, v0
	v_mov_b32_e32 v35, v0
	v_mov_b32_e32 v40, v0
	v_mov_b32_e32 v41, v0
	v_mov_b32_e32 v42, v0
	v_mov_b32_e32 v43, v0
	v_mov_b32_e32 v48, v0
	v_mov_b32_e32 v49, v0
	v_mov_b32_e32 v50, v0
	v_mov_b32_e32 v51, v0
	v_mov_b32_e32 v12, v0
	v_mov_b32_e32 v13, v0
	v_mov_b32_e32 v14, v0
	v_mov_b32_e32 v15, v0
	v_mov_b32_e32 v20, v0
	v_mov_b32_e32 v21, v0
	v_mov_b32_e32 v22, v0
	v_mov_b32_e32 v23, v0
	v_mov_b32_e32 v28, v0
	v_mov_b32_e32 v29, v0
	v_mov_b32_e32 v30, v0
	v_mov_b32_e32 v31, v0
	v_mov_b32_e32 v36, v0
	v_mov_b32_e32 v37, v0
	v_mov_b32_e32 v38, v0
	v_mov_b32_e32 v39, v0
	v_mov_b32_e32 v44, v0
	v_mov_b32_e32 v45, v0
	v_mov_b32_e32 v46, v0
	v_mov_b32_e32 v47, v0
	v_mov_b32_e32 v52, v0
	v_mov_b32_e32 v53, v0
	v_mov_b32_e32 v54, v0
	v_mov_b32_e32 v55, v0
	v_mov_b32_e32 v56, v0
	v_mov_b32_e32 v57, v0
	v_mov_b32_e32 v58, v0
	v_mov_b32_e32 v59, v0
	v_mov_b32_e32 v60, v0
	v_mov_b32_e32 v61, v0
	v_mov_b32_e32 v62, v0
	v_mov_b32_e32 v63, v0
	v_mov_b32_e32 v64, v0
	v_mov_b32_e32 v65, v0
	v_mov_b32_e32 v66, v0
	v_mov_b32_e32 v67, v0
	v_mov_b32_e32 v68, v0
	v_mov_b32_e32 v69, v0
	v_mov_b32_e32 v70, v0
	v_mov_b32_e32 v71, v0
	v_mov_b32_e32 v72, v0
	v_mov_b32_e32 v73, v0
	v_mov_b32_e32 v74, v0
	v_mov_b32_e32 v75, v0
	v_mov_b32_e32 v80, v0
	v_mov_b32_e32 v81, v0
	v_mov_b32_e32 v82, v0
	v_mov_b32_e32 v83, v0
	v_mov_b32_e32 v88, v0
	v_mov_b32_e32 v89, v0
	v_mov_b32_e32 v90, v0
	v_mov_b32_e32 v91, v0
	v_mov_b32_e32 v96, v0
	v_mov_b32_e32 v97, v0
	v_mov_b32_e32 v98, v0
	v_mov_b32_e32 v99, v0
	v_mov_b32_e32 v104, v0
	v_mov_b32_e32 v105, v0
	v_mov_b32_e32 v106, v0
	v_mov_b32_e32 v107, v0
	v_mov_b32_e32 v112, v0
	v_mov_b32_e32 v113, v0
	v_mov_b32_e32 v114, v0
	v_mov_b32_e32 v115, v0
	v_mov_b32_e32 v76, v0
	v_mov_b32_e32 v77, v0
	v_mov_b32_e32 v78, v0
	v_mov_b32_e32 v79, v0
	v_mov_b32_e32 v84, v0
	v_mov_b32_e32 v85, v0
	v_mov_b32_e32 v86, v0
	v_mov_b32_e32 v87, v0
	v_mov_b32_e32 v92, v0
	v_mov_b32_e32 v93, v0
	v_mov_b32_e32 v94, v0
	v_mov_b32_e32 v95, v0
	v_mov_b32_e32 v100, v0
	v_mov_b32_e32 v101, v0
	v_mov_b32_e32 v102, v0
	v_mov_b32_e32 v103, v0
	v_mov_b32_e32 v108, v0
	v_mov_b32_e32 v109, v0
	v_mov_b32_e32 v110, v0
	v_mov_b32_e32 v111, v0
	v_mov_b32_e32 v116, v0
	v_mov_b32_e32 v117, v0
	v_mov_b32_e32 v118, v0
	v_mov_b32_e32 v119, v0
	v_mov_b32_e32 v120, v0
	v_mov_b32_e32 v121, v0
	v_mov_b32_e32 v122, v0
	v_mov_b32_e32 v123, v0
	v_mov_b32_e32 v124, v0
	v_mov_b32_e32 v125, v0
	v_mov_b32_e32 v126, v0
	v_mov_b32_e32 v127, v0
	s_cmp_lt_u32 s89, 4
	s_cbranch_scc0 .Lprio_163
	s_setprio 1

.Lp2_noswap:
	s_add_u32 s30, s30, 0x100080
	s_addc_u32 s31, s31, 0
	s_add_u32 s75, s34, 0x100
	v_mov_b32_e32 v0, 0
	s_addc_u32 s78, s35, 0
	s_mov_b32 s79, -2
	v_mov_b32_e32 v1, v0
	v_mov_b32_e32 v2, v0
	v_mov_b32_e32 v3, v0
	v_mov_b32_e32 v4, v0
	v_mov_b32_e32 v5, v0
	v_mov_b32_e32 v6, v0
	v_mov_b32_e32 v7, v0
	v_mov_b32_e32 v16, v0
	v_mov_b32_e32 v17, v0
	v_mov_b32_e32 v18, v0
	v_mov_b32_e32 v19, v0
	v_mov_b32_e32 v20, v0
	v_mov_b32_e32 v21, v0
	v_mov_b32_e32 v22, v0
	v_mov_b32_e32 v23, v0
	v_mov_b32_e32 v32, v0
	v_mov_b32_e32 v33, v0
	v_mov_b32_e32 v34, v0
	v_mov_b32_e32 v35, v0
	v_mov_b32_e32 v36, v0
	v_mov_b32_e32 v37, v0
	v_mov_b32_e32 v38, v0
	v_mov_b32_e32 v39, v0
	v_mov_b32_e32 v48, v0
	v_mov_b32_e32 v49, v0
	v_mov_b32_e32 v50, v0
	v_mov_b32_e32 v51, v0
	v_mov_b32_e32 v52, v0
	v_mov_b32_e32 v53, v0
	v_mov_b32_e32 v54, v0
	v_mov_b32_e32 v55, v0
	v_mov_b32_e32 v8, v0
	v_mov_b32_e32 v9, v0
	v_mov_b32_e32 v10, v0
	v_mov_b32_e32 v11, v0
	v_mov_b32_e32 v12, v0
	v_mov_b32_e32 v13, v0
	v_mov_b32_e32 v14, v0
	v_mov_b32_e32 v15, v0
	v_mov_b32_e32 v24, v0
	v_mov_b32_e32 v25, v0
	v_mov_b32_e32 v26, v0
	v_mov_b32_e32 v27, v0
	v_mov_b32_e32 v28, v0
	v_mov_b32_e32 v29, v0
	v_mov_b32_e32 v30, v0
	v_mov_b32_e32 v31, v0
	v_mov_b32_e32 v40, v0
	v_mov_b32_e32 v41, v0
	v_mov_b32_e32 v42, v0
	v_mov_b32_e32 v43, v0
	v_mov_b32_e32 v44, v0
	v_mov_b32_e32 v45, v0
	v_mov_b32_e32 v46, v0
	v_mov_b32_e32 v47, v0
	v_mov_b32_e32 v56, v0
	v_mov_b32_e32 v57, v0
	v_mov_b32_e32 v58, v0
	v_mov_b32_e32 v59, v0
	v_mov_b32_e32 v60, v0
	v_mov_b32_e32 v61, v0
	v_mov_b32_e32 v62, v0
	v_mov_b32_e32 v63, v0
	v_mov_b32_e32 v64, v0
	v_mov_b32_e32 v65, v0
	v_mov_b32_e32 v66, v0
	v_mov_b32_e32 v67, v0
	v_mov_b32_e32 v68, v0
	v_mov_b32_e32 v69, v0
	v_mov_b32_e32 v70, v0
	v_mov_b32_e32 v71, v0
	v_mov_b32_e32 v80, v0
	v_mov_b32_e32 v81, v0
	v_mov_b32_e32 v82, v0
	v_mov_b32_e32 v83, v0
	v_mov_b32_e32 v84, v0
	v_mov_b32_e32 v85, v0
	v_mov_b32_e32 v86, v0
	v_mov_b32_e32 v87, v0
	v_mov_b32_e32 v88, v0
	v_mov_b32_e32 v89, v0
	v_mov_b32_e32 v90, v0
	v_mov_b32_e32 v91, v0
	v_mov_b32_e32 v92, v0
	v_mov_b32_e32 v93, v0
	v_mov_b32_e32 v94, v0
	v_mov_b32_e32 v95, v0
	v_mov_b32_e32 v100, v0
	v_mov_b32_e32 v101, v0
	v_mov_b32_e32 v102, v0
	v_mov_b32_e32 v103, v0
	v_mov_b32_e32 v108, v0
	v_mov_b32_e32 v109, v0
	v_mov_b32_e32 v110, v0
	v_mov_b32_e32 v111, v0
	v_mov_b32_e32 v72, v0
	v_mov_b32_e32 v73, v0
	v_mov_b32_e32 v74, v0
	v_mov_b32_e32 v75, v0
	v_mov_b32_e32 v76, v0
	v_mov_b32_e32 v77, v0
	v_mov_b32_e32 v78, v0
	v_mov_b32_e32 v79, v0
	v_mov_b32_e32 v96, v0
	v_mov_b32_e32 v97, v0
	v_mov_b32_e32 v98, v0
	v_mov_b32_e32 v99, v0
	v_mov_b32_e32 v104, v0
	v_mov_b32_e32 v105, v0
	v_mov_b32_e32 v106, v0
	v_mov_b32_e32 v107, v0
	v_mov_b32_e32 v112, v0
	v_mov_b32_e32 v113, v0
	v_mov_b32_e32 v114, v0
	v_mov_b32_e32 v115, v0
	v_mov_b32_e32 v116, v0
	v_mov_b32_e32 v117, v0
	v_mov_b32_e32 v118, v0
	v_mov_b32_e32 v119, v0
	v_mov_b32_e32 v120, v0
	v_mov_b32_e32 v121, v0
	v_mov_b32_e32 v122, v0
	v_mov_b32_e32 v123, v0
	v_mov_b32_e32 v124, v0
	v_mov_b32_e32 v125, v0
	v_mov_b32_e32 v126, v0
	v_mov_b32_e32 v127, v0
	s_cmp_lt_u32 s89, 4
	s_cbranch_scc0 .Lprio_188
	s_setprio 1

.LBB0_430:
	s_ashr_i32 s15, s14, 31
	s_lshl_b64 s[16:17], s[14:15], 21
	s_add_u32 s16, s56, s16
	s_addc_u32 s17, s57, s17
	s_and_b64 s[18:19], s[4:5], exec
	s_cselect_b32 s15, s17, s27
	s_cselect_b32 s21, s16, s26
	s_ashr_i32 s13, s12, 31
	s_lshl_b64 s[18:19], s[12:13], 21
	v_readlane_b32 s30, v254, 5
	v_readlane_b32 s31, v254, 6
	s_add_u32 s18, s30, s18
	s_addc_u32 s19, s31, s19
	s_and_b64 s[30:31], s[4:5], exec
	s_cselect_b32 s13, s19, s29
	s_cselect_b32 s52, s18, s28
	s_add_u32 s26, s26, 0x100080
	s_addc_u32 s27, s27, 0
	s_add_u32 s53, s28, 0x100
	v_mov_b32_e32 v0, 0
	s_addc_u32 s54, s29, 0
	s_mov_b32 s55, -2
	s_waitcnt lgkmcnt(0)
	v_mov_b32_e32 v1, v0
	v_mov_b32_e32 v2, v0
	v_mov_b32_e32 v3, v0
	v_mov_b32_e32 v4, v0
	v_mov_b32_e32 v5, v0
	v_mov_b32_e32 v6, v0
	v_mov_b32_e32 v7, v0
	v_mov_b32_e32 v16, v0
	v_mov_b32_e32 v17, v0
	v_mov_b32_e32 v18, v0
	v_mov_b32_e32 v19, v0
	v_mov_b32_e32 v20, v0
	v_mov_b32_e32 v21, v0
	v_mov_b32_e32 v22, v0
	v_mov_b32_e32 v23, v0
	v_mov_b32_e32 v32, v0
	v_mov_b32_e32 v33, v0
	v_mov_b32_e32 v34, v0
	v_mov_b32_e32 v35, v0
	v_mov_b32_e32 v36, v0
	v_mov_b32_e32 v37, v0
	v_mov_b32_e32 v38, v0
	v_mov_b32_e32 v39, v0
	v_mov_b32_e32 v48, v0
	v_mov_b32_e32 v49, v0
	v_mov_b32_e32 v50, v0
	v_mov_b32_e32 v51, v0
	v_mov_b32_e32 v52, v0
	v_mov_b32_e32 v53, v0
	v_mov_b32_e32 v54, v0
	v_mov_b32_e32 v55, v0
	v_mov_b32_e32 v8, v0
	v_mov_b32_e32 v9, v0
	v_mov_b32_e32 v10, v0
	v_mov_b32_e32 v11, v0
	v_mov_b32_e32 v12, v0
	v_mov_b32_e32 v13, v0
	v_mov_b32_e32 v14, v0
	v_mov_b32_e32 v15, v0
	v_mov_b32_e32 v24, v0
	v_mov_b32_e32 v25, v0
	v_mov_b32_e32 v26, v0
	v_mov_b32_e32 v27, v0
	v_mov_b32_e32 v28, v0
	v_mov_b32_e32 v29, v0
	v_mov_b32_e32 v30, v0
	v_mov_b32_e32 v31, v0
	v_mov_b32_e32 v40, v0
	v_mov_b32_e32 v41, v0
	v_mov_b32_e32 v42, v0
	v_mov_b32_e32 v43, v0
	v_mov_b32_e32 v44, v0
	v_mov_b32_e32 v45, v0
	v_mov_b32_e32 v46, v0
	v_mov_b32_e32 v47, v0
	v_mov_b32_e32 v56, v0
	v_mov_b32_e32 v57, v0
	v_mov_b32_e32 v58, v0
	v_mov_b32_e32 v59, v0
	v_mov_b32_e32 v60, v0
	v_mov_b32_e32 v61, v0
	v_mov_b32_e32 v62, v0
	v_mov_b32_e32 v63, v0
	v_mov_b32_e32 v64, v0
	v_mov_b32_e32 v65, v0
	v_mov_b32_e32 v66, v0
	v_mov_b32_e32 v67, v0
	v_mov_b32_e32 v68, v0
	v_mov_b32_e32 v69, v0
	v_mov_b32_e32 v70, v0
	v_mov_b32_e32 v71, v0
	v_mov_b32_e32 v80, v0
	v_mov_b32_e32 v81, v0
	v_mov_b32_e32 v82, v0
	v_mov_b32_e32 v83, v0
	v_mov_b32_e32 v84, v0
	v_mov_b32_e32 v85, v0
	v_mov_b32_e32 v86, v0
	v_mov_b32_e32 v87, v0
	v_mov_b32_e32 v96, v0
	v_mov_b32_e32 v97, v0
	v_mov_b32_e32 v98, v0
	v_mov_b32_e32 v99, v0
	v_mov_b32_e32 v100, v0
	v_mov_b32_e32 v101, v0
	v_mov_b32_e32 v102, v0
	v_mov_b32_e32 v103, v0
	v_mov_b32_e32 v112, v0
	v_mov_b32_e32 v113, v0
	v_mov_b32_e32 v114, v0
	v_mov_b32_e32 v115, v0
	v_mov_b32_e32 v116, v0
	v_mov_b32_e32 v117, v0
	v_mov_b32_e32 v118, v0
	v_mov_b32_e32 v119, v0
	v_mov_b32_e32 v72, v0
	v_mov_b32_e32 v73, v0
	v_mov_b32_e32 v74, v0
	v_mov_b32_e32 v75, v0
	v_mov_b32_e32 v76, v0
	v_mov_b32_e32 v77, v0
	v_mov_b32_e32 v78, v0
	v_mov_b32_e32 v79, v0
	v_mov_b32_e32 v88, v0
	v_mov_b32_e32 v89, v0
	v_mov_b32_e32 v90, v0
	v_mov_b32_e32 v91, v0
	v_mov_b32_e32 v92, v0
	v_mov_b32_e32 v93, v0
	v_mov_b32_e32 v94, v0
	v_mov_b32_e32 v95, v0
	v_mov_b32_e32 v104, v0
	v_mov_b32_e32 v105, v0
	v_mov_b32_e32 v106, v0
	v_mov_b32_e32 v107, v0
	v_mov_b32_e32 v108, v0
	v_mov_b32_e32 v109, v0
	v_mov_b32_e32 v110, v0
	v_mov_b32_e32 v111, v0
	v_mov_b32_e32 v120, v0
	v_mov_b32_e32 v121, v0
	v_mov_b32_e32 v122, v0
	v_mov_b32_e32 v123, v0
	v_mov_b32_e32 v124, v0
	v_mov_b32_e32 v125, v0
	v_mov_b32_e32 v126, v0
	v_mov_b32_e32 v127, v0
	s_cmp_lt_u32 s89, 4
	s_cbranch_scc0 .Lprio_431
	s_setprio 1

.LBB0_527:
	s_ashr_i32 s47, s46, 31
	s_lshl_b64 s[50:51], s[46:47], 21
	s_add_u32 s50, s42, s50
	s_addc_u32 s51, s43, s51
	s_and_b64 s[52:53], s[18:19], exec
	s_cselect_b32 s47, s51, s21
	s_cselect_b32 s57, s50, s20
	s_ashr_i32 s41, s40, 31
	s_lshl_b64 s[52:53], s[40:41], 21
	s_add_u32 s52, s76, s52
	s_addc_u32 s53, s77, s53
	s_and_b64 s[78:79], s[18:19], exec
	s_cselect_b32 s41, s53, s63
	s_cselect_b32 s59, s52, s62
	s_add_u32 s20, s20, 0x100080
	s_addc_u32 s21, s21, 0
	s_add_u32 s81, s62, 0x100
	v_mov_b32_e32 v8, 0
	s_addc_u32 s82, s63, 0
	s_mov_b32 s83, -2
	v_mov_b32_e32 v9, v8
	v_mov_b32_e32 v10, v8
	v_mov_b32_e32 v11, v8
	v_mov_b32_e32 v4, v8
	v_mov_b32_e32 v5, v8
	v_mov_b32_e32 v6, v8
	v_mov_b32_e32 v7, v8
	v_mov_b32_e32 v12, v8
	v_mov_b32_e32 v13, v8
	v_mov_b32_e32 v14, v8
	v_mov_b32_e32 v15, v8
	v_mov_b32_e32 v16, v8
	v_mov_b32_e32 v17, v8
	v_mov_b32_e32 v18, v8
	v_mov_b32_e32 v19, v8
	v_mov_b32_e32 v20, v8
	v_mov_b32_e32 v21, v8
	v_mov_b32_e32 v22, v8
	v_mov_b32_e32 v23, v8
	v_mov_b32_e32 v24, v8
	v_mov_b32_e32 v25, v8
	v_mov_b32_e32 v26, v8
	v_mov_b32_e32 v27, v8
	v_mov_b32_e32 v28, v8
	v_mov_b32_e32 v29, v8
	v_mov_b32_e32 v30, v8
	v_mov_b32_e32 v31, v8
	v_mov_b32_e32 v32, v8
	v_mov_b32_e32 v33, v8
	v_mov_b32_e32 v34, v8
	v_mov_b32_e32 v35, v8
	v_mov_b32_e32 v78, v8
	v_mov_b32_e32 v79, v8
	v_mov_b32_e32 v80, v8
	v_mov_b32_e32 v81, v8
	v_mov_b32_e32 v74, v8
	v_mov_b32_e32 v75, v8
	v_mov_b32_e32 v76, v8
	v_mov_b32_e32 v77, v8
	v_mov_b32_e32 v68, v8
	v_mov_b32_e32 v69, v8
	v_mov_b32_e32 v70, v8
	v_mov_b32_e32 v71, v8
	v_mov_b32_e32 v82, v8
	v_mov_b32_e32 v83, v8
	v_mov_b32_e32 v84, v8
	v_mov_b32_e32 v85, v8
	v_mov_b32_e32 v86, v8
	v_mov_b32_e32 v87, v8
	v_mov_b32_e32 v88, v8
	v_mov_b32_e32 v89, v8
	v_mov_b32_e32 v90, v8
	v_mov_b32_e32 v91, v8
	v_mov_b32_e32 v92, v8
	v_mov_b32_e32 v93, v8
	v_mov_b32_e32 v94, v8
	v_mov_b32_e32 v95, v8
	v_mov_b32_e32 v96, v8
	v_mov_b32_e32 v97, v8
	v_mov_b32_e32 v98, v8
	v_mov_b32_e32 v99, v8
	v_mov_b32_e32 v100, v8
	v_mov_b32_e32 v101, v8
	v_mov_b32_e32 v36, v8
	v_mov_b32_e32 v37, v8
	v_mov_b32_e32 v38, v8
	v_mov_b32_e32 v39, v8
	v_mov_b32_e32 v40, v8
	v_mov_b32_e32 v41, v8
	v_mov_b32_e32 v42, v8
	v_mov_b32_e32 v43, v8
	v_mov_b32_e32 v44, v8
	v_mov_b32_e32 v45, v8
	v_mov_b32_e32 v46, v8
	v_mov_b32_e32 v47, v8
	v_mov_b32_e32 v48, v8
	v_mov_b32_e32 v49, v8
	v_mov_b32_e32 v50, v8
	v_mov_b32_e32 v51, v8
	v_mov_b32_e32 v52, v8
	v_mov_b32_e32 v53, v8
	v_mov_b32_e32 v54, v8
	v_mov_b32_e32 v55, v8
	v_mov_b32_e32 v56, v8
	v_mov_b32_e32 v57, v8
	v_mov_b32_e32 v58, v8
	v_mov_b32_e32 v59, v8
	v_mov_b32_e32 v60, v8
	v_mov_b32_e32 v61, v8
	v_mov_b32_e32 v62, v8
	v_mov_b32_e32 v63, v8
	v_mov_b32_e32 v64, v8
	v_mov_b32_e32 v65, v8
	v_mov_b32_e32 v66, v8
	v_mov_b32_e32 v67, v8
	v_mov_b32_e32 v102, v8
	v_mov_b32_e32 v103, v8
	v_mov_b32_e32 v104, v8
	v_mov_b32_e32 v105, v8
	v_mov_b32_e32 v106, v8
	v_mov_b32_e32 v107, v8
	v_mov_b32_e32 v108, v8
	v_mov_b32_e32 v109, v8
	v_mov_b32_e32 v110, v8
	v_mov_b32_e32 v111, v8
	v_mov_b32_e32 v112, v8
	v_mov_b32_e32 v113, v8
	v_mov_b32_e32 v114, v8
	v_mov_b32_e32 v115, v8
	v_mov_b32_e32 v116, v8
	v_mov_b32_e32 v117, v8
	v_mov_b32_e32 v118, v8
	v_mov_b32_e32 v119, v8
	v_mov_b32_e32 v120, v8
	v_mov_b32_e32 v121, v8
	v_mov_b32_e32 v122, v8
	v_mov_b32_e32 v123, v8
	v_mov_b32_e32 v124, v8
	v_mov_b32_e32 v125, v8
	v_mov_b32_e32 v126, v8
	v_mov_b32_e32 v127, v8
	v_mov_b32_e32 v128, v8
	v_mov_b32_e32 v129, v8
	v_mov_b32_e32 v130, v8
	v_mov_b32_e32 v131, v8
	v_mov_b32_e32 v132, v8
	v_mov_b32_e32 v133, v8
	s_cmp_lt_u32 s89, 4
	s_cbranch_scc0 .Lprio_528
	s_setprio 1

.LBB0_814:
	s_ashr_i32 s29, s28, 31
	s_lshl_b64 s[34:35], s[28:29], 22
	s_add_u32 s34, s48, s34
	s_addc_u32 s35, s49, s35
	s_and_b64 s[36:37], s[4:5], exec
	s_cselect_b32 s29, s35, s47
	s_cselect_b32 s39, s34, s46
	s_ashr_i32 s31, s30, 31
	s_lshl_b64 s[36:37], s[30:31], 22
	v_readlane_b32 s52, v254, 7
	v_readlane_b32 s53, v254, 8
	s_add_u32 s36, s52, s36
	s_addc_u32 s37, s53, s37
	s_and_b64 s[52:53], s[4:5], exec
	s_cselect_b32 s31, s37, s51
	s_cselect_b32 s41, s36, s50
	s_add_u32 s46, s46, 0x200080
	s_addc_u32 s47, s47, 0
	s_add_u32 s75, s50, 0x100
	v_mov_b32_e32 v0, 0
	s_addc_u32 s76, s51, 0
	s_mov_b32 s77, -2
	v_mov_b32_e32 v1, v0
	v_mov_b32_e32 v2, v0
	v_mov_b32_e32 v3, v0
	v_mov_b32_e32 v4, v0
	v_mov_b32_e32 v5, v0
	v_mov_b32_e32 v6, v0
	v_mov_b32_e32 v7, v0
	v_mov_b32_e32 v16, v0
	v_mov_b32_e32 v17, v0
	v_mov_b32_e32 v18, v0
	v_mov_b32_e32 v19, v0
	v_mov_b32_e32 v20, v0
	v_mov_b32_e32 v21, v0
	v_mov_b32_e32 v22, v0
	v_mov_b32_e32 v23, v0
	v_mov_b32_e32 v32, v0
	v_mov_b32_e32 v33, v0
	v_mov_b32_e32 v34, v0
	v_mov_b32_e32 v35, v0
	v_mov_b32_e32 v36, v0
	v_mov_b32_e32 v37, v0
	v_mov_b32_e32 v38, v0
	v_mov_b32_e32 v39, v0
	v_mov_b32_e32 v48, v0
	v_mov_b32_e32 v49, v0
	v_mov_b32_e32 v50, v0
	v_mov_b32_e32 v51, v0
	v_mov_b32_e32 v52, v0
	v_mov_b32_e32 v53, v0
	v_mov_b32_e32 v54, v0
	v_mov_b32_e32 v55, v0
	v_mov_b32_e32 v8, v0
	v_mov_b32_e32 v9, v0
	v_mov_b32_e32 v10, v0
	v_mov_b32_e32 v11, v0
	v_mov_b32_e32 v12, v0
	v_mov_b32_e32 v13, v0
	v_mov_b32_e32 v14, v0
	v_mov_b32_e32 v15, v0
	v_mov_b32_e32 v24, v0
	v_mov_b32_e32 v25, v0
	v_mov_b32_e32 v26, v0
	v_mov_b32_e32 v27, v0
	v_mov_b32_e32 v28, v0
	v_mov_b32_e32 v29, v0
	v_mov_b32_e32 v30, v0
	v_mov_b32_e32 v31, v0
	v_mov_b32_e32 v40, v0
	v_mov_b32_e32 v41, v0
	v_mov_b32_e32 v42, v0
	v_mov_b32_e32 v43, v0
	v_mov_b32_e32 v44, v0
	v_mov_b32_e32 v45, v0
	v_mov_b32_e32 v46, v0
	v_mov_b32_e32 v47, v0
	v_mov_b32_e32 v72, v0
	v_mov_b32_e32 v73, v0
	v_mov_b32_e32 v74, v0
	v_mov_b32_e32 v75, v0
	v_mov_b32_e32 v76, v0
	v_mov_b32_e32 v77, v0
	v_mov_b32_e32 v78, v0
	v_mov_b32_e32 v79, v0
	v_mov_b32_e32 v80, v0
	v_mov_b32_e32 v81, v0
	v_mov_b32_e32 v82, v0
	v_mov_b32_e32 v83, v0
	v_mov_b32_e32 v84, v0
	v_mov_b32_e32 v85, v0
	v_mov_b32_e32 v86, v0
	v_mov_b32_e32 v87, v0
	v_mov_b32_e32 v96, v0
	v_mov_b32_e32 v97, v0
	v_mov_b32_e32 v98, v0
	v_mov_b32_e32 v99, v0
	v_mov_b32_e32 v100, v0
	v_mov_b32_e32 v101, v0
	v_mov_b32_e32 v102, v0
	v_mov_b32_e32 v103, v0
	v_mov_b32_e32 v112, v0
	v_mov_b32_e32 v113, v0
	v_mov_b32_e32 v114, v0
	v_mov_b32_e32 v115, v0
	v_mov_b32_e32 v116, v0
	v_mov_b32_e32 v117, v0
	v_mov_b32_e32 v118, v0
	v_mov_b32_e32 v119, v0
	v_mov_b32_e32 v128, v0
	v_mov_b32_e32 v129, v0
	v_mov_b32_e32 v130, v0
	v_mov_b32_e32 v131, v0
	v_mov_b32_e32 v132, v0
	v_mov_b32_e32 v133, v0
	v_mov_b32_e32 v134, v0
	v_mov_b32_e32 v135, v0
	v_mov_b32_e32 v88, v0
	v_mov_b32_e32 v89, v0
	v_mov_b32_e32 v90, v0
	v_mov_b32_e32 v91, v0
	v_mov_b32_e32 v92, v0
	v_mov_b32_e32 v93, v0
	v_mov_b32_e32 v94, v0
	v_mov_b32_e32 v95, v0
	v_mov_b32_e32 v104, v0
	v_mov_b32_e32 v105, v0
	v_mov_b32_e32 v106, v0
	v_mov_b32_e32 v107, v0
	v_mov_b32_e32 v108, v0
	v_mov_b32_e32 v109, v0
	v_mov_b32_e32 v110, v0
	v_mov_b32_e32 v111, v0
	v_mov_b32_e32 v120, v0
	v_mov_b32_e32 v121, v0
	v_mov_b32_e32 v122, v0
	v_mov_b32_e32 v123, v0
	v_mov_b32_e32 v124, v0
	v_mov_b32_e32 v125, v0
	v_mov_b32_e32 v126, v0
	v_mov_b32_e32 v127, v0
	v_mov_b32_e32 v136, v0
	v_mov_b32_e32 v137, v0
	v_mov_b32_e32 v138, v0
	v_mov_b32_e32 v139, v0
	v_mov_b32_e32 v140, v0
	v_mov_b32_e32 v141, v0
	v_mov_b32_e32 v142, v0
	v_mov_b32_e32 v143, v0
	s_cmp_lt_u32 s89, 4
	s_cbranch_scc0 .Lprio_815
	s_setprio 1
